# pool mixer moved from the start of the state-GEMM phase into the carry-scan phase, run by the six waves per workgroup that were idle there (waves 0-1 scan)
# speedup vs baseline: 1.0009x; 1.0009x over previous
; __device__ __forceinline__ unsigned cvt_pk_bf16(float lo, float hi) { unsigned r; asm volatile("v_cvt_pk_bf16_f32 %0, %1, %2" : "=v"(r) : "v"(lo), "v"(hi)); return r; }
; __device__ __forceinline__ float bf_lo(unsigned w) { return __uint_as_float(w << 16); }
; __device__ __forceinline__ float bf_hi(unsigned w) { return __uint_as_float(w & 0xffff0000u); }
; __device__ __forceinline__ void pool_phase(const bf16_t* ZP, bf16_t* CAT, int gw, int NGW, int lane) {
;     const int gi = lane >> 4, w = 2 << gi, lo = w >> 1, hi = w - 1 - lo;
;     for (int row = gw; row < MTOK; row += NGW) {
;         const int tl = row & (SEQL - 1); float acc[8];
; #pragma unroll
;         for (int j = 0; j < 8; ++j) acc[j] = 0.f;
;         const int d0 = -min(lo, tl), d1 = min(hi, SEQL - 1 - tl);
; #pragma unroll
;         for (int d = -8; d <= 7; ++d) if (d >= d0 && d <= d1) { const u32x4 z = *(const u32x4*)(ZP + (size_t)(row + d) * 512 + lane * 8);
;             acc[0] += bf_lo(z.x); acc[1] += bf_hi(z.x); acc[2] += bf_lo(z.y); acc[3] += bf_hi(z.y); acc[4] += bf_lo(z.z); acc[5] += bf_hi(z.z); acc[6] += bf_lo(z.w); acc[7] += bf_hi(z.w); }
;         const float inv = 1.0f / (float)(d1 - d0 + 1); const u32x4 z = *(const u32x4*)(ZP + (size_t)row * 512 + lane * 8);
;         u32x4 o; o.x = cvt_pk_bf16(acc[0] * inv - bf_lo(z.x), acc[1] * inv - bf_hi(z.x)); o.y = cvt_pk_bf16(acc[2] * inv - bf_lo(z.y), acc[3] * inv - bf_hi(z.y));
;         o.z = cvt_pk_bf16(acc[4] * inv - bf_lo(z.z), acc[5] * inv - bf_hi(z.z)); o.w = cvt_pk_bf16(acc[6] * inv - bf_lo(z.w), acc[7] * inv - bf_hi(z.w));
;         *(u32x4*)(CAT + (size_t)row * 1024 + lane * 8) = o;
;     }
; }
; __global__ void __launch_bounds__(NTHR, 2) fwd_megakernel(Args kargs) {
;     ...
;                     PH_BEGIN
;                         for (int rep = 0; rep < DUP_PC; ++rep) pool_phase(FB, SCR, gw, NGW, lane);
;                         pg8::Gemm g{ZS, (const bf16_t*)(ws + WS_WST + (size_t)mi * 32 * SZ_WST), NCHUNK, 256, 512, 768, 512, (size_t)NCHUNK * 768 * 2, SZ_WST}; BatchOrder S; S.init(NCHUNK, 256, 32, G, bx);
;                         EpiState E{SLOC};
;                         for (int rep = 0; rep < DUP_MIX; ++rep) { pg8::gemm_phase<EpiState, BatchOrder, GEMM_ALIGN, GEMM_SP2>(lds, g, S, E); }
.LBB0_736:
	s_cmp_ge_i32 s26, s86
	s_cselect_b64 s[10:11], -1, 0
	s_and_b64 s[0:1], s[10:11], s[0:1]
	s_andn2_b64 vcc, exec, s[0:1]
	s_cbranch_vccnz .LBB0_792
	s_mov_b64 s[0:1], s[82:83]
	v_mov_b32_e32 v0, v202
	s_load_dwordx4 s[44:47], s[0:1], 0xb0
	v_readfirstlane_b32 s8, v0
	s_ashr_i32 s0, s8, 6
	v_readlane_b32 s1, v254, 41
	s_add_i32 s8, s0, s1
	s_cmp_gt_i32 s8, 0xffff
	s_branch .LBB0_772

; __device__ __forceinline__ unsigned cvt_pk_bf16(float lo, float hi) { unsigned r; asm volatile("v_cvt_pk_bf16_f32 %0, %1, %2" : "=v"(r) : "v"(lo), "v"(hi)); return r; }
; __device__ __forceinline__ float bf_lo(unsigned w) { return __uint_as_float(w << 16); }
; __device__ __forceinline__ float bf_hi(unsigned w) { return __uint_as_float(w & 0xffff0000u); }
; __device__ __forceinline__ void pool_phase(const bf16_t* ZP, bf16_t* CAT, int gw, int NGW, int lane) {
;     const int gi = lane >> 4, w = 2 << gi, lo = w >> 1, hi = w - 1 - lo;
;     for (int row = gw; row < MTOK; row += NGW) {
;         const int tl = row & (SEQL - 1); float acc[8];
; #pragma unroll
;         for (int j = 0; j < 8; ++j) acc[j] = 0.f;
;         const int d0 = -min(lo, tl), d1 = min(hi, SEQL - 1 - tl);
; #pragma unroll
;         for (int d = -8; d <= 7; ++d) if (d >= d0 && d <= d1) { const u32x4 z = *(const u32x4*)(ZP + (size_t)(row + d) * 512 + lane * 8);
;             acc[0] += bf_lo(z.x); acc[1] += bf_hi(z.x); acc[2] += bf_lo(z.y); acc[3] += bf_hi(z.y); acc[4] += bf_lo(z.z); acc[5] += bf_hi(z.z); acc[6] += bf_lo(z.w); acc[7] += bf_hi(z.w); }
;         const float inv = 1.0f / (float)(d1 - d0 + 1); const u32x4 z = *(const u32x4*)(ZP + (size_t)row * 512 + lane * 8);
;         u32x4 o; o.x = cvt_pk_bf16(acc[0] * inv - bf_lo(z.x), acc[1] * inv - bf_hi(z.x)); o.y = cvt_pk_bf16(acc[2] * inv - bf_lo(z.y), acc[3] * inv - bf_hi(z.y));
;         o.z = cvt_pk_bf16(acc[4] * inv - bf_lo(z.z), acc[5] * inv - bf_hi(z.z)); o.w = cvt_pk_bf16(acc[6] * inv - bf_lo(z.w), acc[7] * inv - bf_hi(z.w));
;         *(u32x4*)(CAT + (size_t)row * 1024 + lane * 8) = o;
; __global__ void __launch_bounds__(NTHR, 2) fwd_megakernel(Args kargs) {
;     ...
;                     PH_BEGIN
;                         for (int rep = 0; rep < DUP_PC; ++rep) { carry_phase(a, mi, wave, lane, G); }
.LBB0_860:
	s_cmp_ge_i32 s26, s86
	s_cselect_b64 s[28:29], -1, 0
	s_and_b64 s[0:1], s[28:29], s[0:1]
	s_andn2_b64 vcc, exec, s[0:1]
	s_cbranch_vccnz .LBB0_877
	v_readfirstlane_b32 s8, v202
	s_nop 3
	s_ashr_i32 s0, s8, 6
	s_cmp_lt_u32 s0, 2
	s_cbranch_scc1 .Lc_nopool
	s_load_dwordx4 s[44:47], s[82:83], 0xb0
	s_add_i32 s0, s0, -2
	s_mul_i32 s1, s2, 6
	s_add_i32 s8, s0, s1
	s_waitcnt lgkmcnt(0)
	s_add_u32 s12, s46, 0x8000000
	s_addc_u32 s13, s47, 0
	s_mov_b32 s0, s8
	s_mov_b32 s1, 0
	s_lshl_b64 s[14:15], s[0:1], 11
	s_add_u32 s14, s44, s14
	s_addc_u32 s15, s45, s15
	s_lshl_b64 s[0:1], s[0:1], 10
	s_add_u32 s0, s12, s0
	s_addc_u32 s1, s13, s1
	v_and_b32_e32 v2, 63, v202
	v_bfe_u32 v0, v202, 4, 2
	v_lshlrev_b32_e64 v0, v0, 2
	v_lshrrev_b32_e32 v18, 1, v0
	v_xad_u32 v19, v18, -1, v0
	v_lshlrev_b32_e32 v0, 4, v2
	v_lshl_add_u64 v[2:3], s[12:13], 0, v[0:1]
	v_lshl_add_u64 v[4:5], s[14:15], 0, v[0:1]
	v_lshl_add_u64 v[6:7], s[0:1], 0, v[0:1]
	s_branch .LBB0_740
.LBB0_739:
	s_or_b64 exec, exec, s[0:1]
	v_add3_u32 v0, v0, v16, 1
	v_cvt_f32_i32_e32 v0, v0
	s_add_i32 s8, s8, 0x600
	s_cmp_lt_i32 s8, 0x10000
	v_div_scale_f32 v16, s[0:1], v0, v0, 1.0
	v_rcp_f32_e32 v17, v16
	v_div_scale_f32 v24, vcc, 1.0, v0, 1.0
	v_fma_f32 v25, -v16, v17, 1.0
	v_fmac_f32_e32 v17, v25, v17
	v_mul_f32_e32 v25, v24, v17
	v_fma_f32 v26, -v16, v25, v24
	v_fmac_f32_e32 v25, v26, v17
	v_fma_f32 v16, -v16, v25, v24
	v_div_fmas_f32 v16, v16, v17, v25
	v_div_fixup_f32 v0, v16, v0, 1.0
	s_mov_b64 s[0:1], 0x300000
	s_waitcnt vmcnt(0)
	v_lshlrev_b32_e32 v16, 16, v162
	v_and_b32_e32 v17, 0xffff0000, v162
	v_lshlrev_b32_e32 v20, 16, v163
	v_and_b32_e32 v21, 0xffff0000, v163
	v_lshlrev_b32_e32 v24, 16, v164
	v_and_b32_e32 v22, 0xffff0000, v164
	v_lshlrev_b32_e32 v25, 16, v165
	v_and_b32_e32 v23, 0xffff0000, v165
	v_fma_f32 v8, v0, v8, -v16
	v_fma_f32 v9, v0, v9, -v17
	v_fma_f32 v10, v0, v10, -v20
	v_fma_f32 v11, v0, v11, -v21
	v_fma_f32 v12, v0, v12, -v24
	v_fma_f32 v13, v0, v13, -v22
	v_fma_f32 v14, v0, v14, -v25
	v_fma_f32 v0, v0, v15, -v23
	v_cvt_pk_bf16_f32 v8, v8, v9
	v_cvt_pk_bf16_f32 v9, v10, v11
	v_cvt_pk_bf16_f32 v10, v12, v13
	v_cvt_pk_bf16_f32 v11, v14, v0
	global_store_dwordx4 v[4:5], v[8:11], off
	v_lshl_add_u64 v[4:5], v[4:5], 0, s[0:1]
	s_mov_b64 s[0:1], 0x180000
	s_nop 1
	v_lshl_add_u64 v[6:7], v[6:7], 0, s[0:1]
	s_cbranch_scc0 .Lc_nopool

; __device__ __forceinline__ void carry_phase(ArgsP a, int i, int wave, int lane, int G) {
;     const float* __restrict__ SL = (const float*)(a->ws + WS_SLOC); bf16_t* __restrict__ ZS = (bf16_t*)(a->ws + WS_ZS); const float2* LP = (const float2*)(a->ws + WS_LAMPOW);
;     for (int item = wave * G + (int)blockIdx.x; item < 512; item += NWAV * G) {
;         const int dir = item & 1, b = (item >> 1) & 7, g = item >> 4, q = (i * 2 + dir) * 32 + g, p = lane;
;         const float2 lt = LP[(size_t)(q * 33 + 32) * 64 + p]; float cr = 0.f, ci = 0.f;
;         const size_t rbase = (size_t)g * NCHUNK + b * 256;
.Lc_nopool:
	s_mov_b64 s[42:43], s[82:83]
	v_mov_b32_e32 v28, v202
	s_nop 0
	v_readfirstlane_b32 s0, v28
	s_ashr_i32 s0, s0, 6
	s_mul_i32 s0, s0, s50
	s_add_i32 s54, s0, s2
	s_cmpk_gt_i32 s54, 0x1ff
	s_cbranch_scc1 .LBB0_866
	s_waitcnt lgkmcnt(0)
	s_load_dwordx2 s[18:19], s[42:43], 0xb8
	v_and_b32_e32 v6, 63, v28
	v_lshlrev_b32_e32 v0, 3, v6
	s_mov_b64 s[0:1], 0x35d00000
	v_readlane_b32 s8, v255, 15
	s_waitcnt lgkmcnt(0)
	v_lshl_add_u64 v[2:3], s[18:19], 0, v[0:1]
	v_lshl_add_u64 v[2:3], v[2:3], 0, s[0:1]
	s_and_b32 s0, s54, 1
	s_lshl_b32 s1, s0, 5
	s_or_b32 s55, s1, s8
	v_lshlrev_b32_e32 v0, 2, v6
	s_cmp_eq_u32 s0, 0
	v_lshl_add_u64 v[4:5], s[18:19], 0, v[0:1]
	s_cselect_b64 s[30:31], -1, 0
	s_lshl_b32 s26, s0, 9
	s_lshl_b32 s8, s0, 7
	v_lshl_add_u64 v[4:5], v[4:5], 0, s[26:27]
	s_mov_b64 s[0:1], 0x16000000
	v_lshl_add_u64 v[4:5], v[4:5], 0, s[0:1]
	s_lshl_b32 s26, s8, 1
	v_lshlrev_b32_e32 v0, 1, v6
